# memory cross-attention: s_setprio 1/0 around each tile pair's MFMA group (as the compiled baseline code had)
# baseline (speedup 1.0000x reference)
; __device__ __forceinline__ f32x4 mfma16(bf16x8 a, bf16x8 b, f32x4 c) { return __builtin_amdgcn_mfma_f32_16x16x32_bf16(a, b, c, 0, 0, 0); }
; __device__ __forceinline__ void mem_task(bf16_t* zb, const bf16_t* kvm_b, const bf16_t* vmt_b, int hm, int t0, int lane, bool do_store) {
;     const int n = lane & 15, fq = lane >> 4;
;     bf16_t* qp = zb + (size_t)(t0 + n) * ZM + ZC_QM + hm * 256;
;     bf16x8 qf[8];
; #pragma unroll
;     for (int kk = 0; kk < 8; ++kk) qf[kk] = *(const bf16x8*)(qp + kk * 32 + 8 * fq);
;     f32x4 zero4 = {0.f, 0.f, 0.f, 0.f}; asm volatile("" : "+v"(zero4));
;     f32x4 s[16];
;     const bf16_t* kbase = kvm_b + (size_t)(8 * (n >> 2) + (n & 3)) * 2048 + hm * 256 + 8 * fq;
;     bf16x8 kfr[3][8];
; #pragma unroll
;     for (int kk = 0; kk < 8; ++kk) kfr[0][kk] = *(const bf16x8*)(kbase + kk * 32);
;     { const bf16_t* kp = kbase + (size_t)4 * 2048;
; #pragma unroll
;       for (int kk = 0; kk < 8; ++kk) kfr[1][kk] = *(const bf16x8*)(kp + kk * 32); }
; #pragma unroll
;     for (int kt = 0; kt < 16; ++kt) {
;         if (kt + 2 < 16) { const bf16_t* kp = kbase + (size_t)(((kt + 2) >> 1) * 32 + 4 * ((kt + 2) & 1)) * 2048;
; #pragma unroll
;             for (int kk = 0; kk < 8; ++kk) kfr[(kt + 2) % 3][kk] = *(const bf16x8*)(kp + kk * 32); }
;         f32x4 acc = zero4;
;         __builtin_amdgcn_s_setprio(1);
; #pragma unroll
;         for (int kk = 0; kk < 8; ++kk) acc = mfma16(kfr[kt % 3][kk], qf[kk], acc);
;         __builtin_amdgcn_s_setprio(0);
;         s[kt] = acc; }
.LBB0_366:
	v_and_or_b32 v186, s0, -16, v65
	v_mov_b64_e32 v[188:189], s[78:79]
	s_and_b32 s2, s3, 0x300
	v_mad_i64_i32 v[188:189], s[6:7], v186, s11, v[188:189]
	s_lshl_b32 s38, s2, 1
	v_lshl_add_u64 v[188:189], v[188:189], 0, s[38:39]
	v_lshl_add_u64 v[184:185], v[188:189], 0, s[16:17]
	v_mov_b32_e32 v143, v64
	v_mov_b32_e32 v145, v64
	v_lshl_add_u64 v[188:189], v[184:185], 0, v[142:143]
	global_load_dwordx4 v[0:3], v[188:189], off
	global_load_dwordx4 v[4:7], v[188:189], off offset:64
	global_load_dwordx4 v[8:11], v[188:189], off offset:128
	global_load_dwordx4 v[12:15], v[188:189], off offset:192
	global_load_dwordx4 v[16:19], v[188:189], off offset:256
	global_load_dwordx4 v[20:23], v[188:189], off offset:320
	global_load_dwordx4 v[24:27], v[188:189], off offset:384
	global_load_dwordx4 v[28:31], v[188:189], off offset:448
	v_lshl_add_u64 v[184:185], v[184:185], 0, v[144:145]
	s_lshl_b32 s98, s2, 9
	s_mov_b32 s99, 0
	v_lshl_add_u64 v[180:181], v[66:67], 0, s[98:99]
	v_lshl_add_u64 v[182:183], v[140:141], 0, s[98:99]
	s_lshl_b32 s7, s89, 10
	s_sub_u32 s98, s7, 0x1000
	s_subb_u32 s99, 0, 0
	v_lshl_add_u64 v[180:181], v[180:181], 0, s[98:99]
	v_lshl_add_u64 v[182:183], v[182:183], 0, s[98:99]
	v_lshlrev_b32_e32 v178, 4, v204
	v_add_u32_e32 v179, 0x10000, v178
	s_mov_b64 s[98:99], 0x2000
	s_add_i32 m0, s7, 0
	s_nop 0
	global_load_lds_dwordx4 v[180:181], off
	v_lshl_add_u64 v[180:181], v[180:181], 0, s[98:99]
	s_add_i32 m0, s7, 8192
	s_nop 0
	global_load_lds_dwordx4 v[180:181], off
	v_lshl_add_u64 v[180:181], v[180:181], 0, s[98:99]
	s_add_i32 m0, s7, 16384
	s_nop 0
	global_load_lds_dwordx4 v[180:181], off
	v_lshl_add_u64 v[180:181], v[180:181], 0, s[98:99]
	s_add_i32 m0, s7, 24576
	s_nop 0
	global_load_lds_dwordx4 v[180:181], off
	v_lshl_add_u64 v[180:181], v[180:181], 0, s[98:99]
	s_add_i32 m0, s7, 32768
	s_nop 0
	global_load_lds_dwordx4 v[180:181], off
	v_lshl_add_u64 v[180:181], v[180:181], 0, s[98:99]
	s_add_i32 m0, s7, 40960
	s_nop 0
	global_load_lds_dwordx4 v[180:181], off
	v_lshl_add_u64 v[180:181], v[180:181], 0, s[98:99]
	s_add_i32 m0, s7, 49152
	s_nop 0
	global_load_lds_dwordx4 v[180:181], off
	v_lshl_add_u64 v[180:181], v[180:181], 0, s[98:99]
	s_add_i32 m0, s7, 57344
	s_nop 0
	global_load_lds_dwordx4 v[180:181], off
	v_lshl_add_u64 v[180:181], v[180:181], 0, s[98:99]
	s_add_i32 m0, s7, 65536
	s_nop 0
	global_load_lds_dwordx4 v[180:181], off
	v_lshl_add_u64 v[180:181], v[180:181], 0, s[98:99]
	s_add_i32 m0, s7, 73728
	s_nop 0
	global_load_lds_dwordx4 v[180:181], off
	v_lshl_add_u64 v[180:181], v[180:181], 0, s[98:99]
	s_add_i32 m0, s7, 81920
	s_nop 0
	global_load_lds_dwordx4 v[180:181], off
	v_lshl_add_u64 v[180:181], v[180:181], 0, s[98:99]
	s_add_i32 m0, s7, 90112
	s_nop 0
	global_load_lds_dwordx4 v[180:181], off
	v_lshl_add_u64 v[180:181], v[180:181], 0, s[98:99]
	s_add_i32 m0, s7, 98304
	s_nop 0
	global_load_lds_dwordx4 v[180:181], off
	v_lshl_add_u64 v[180:181], v[180:181], 0, s[98:99]
	s_add_i32 m0, s7, 106496
	s_nop 0
	global_load_lds_dwordx4 v[180:181], off
	v_lshl_add_u64 v[180:181], v[180:181], 0, s[98:99]
	s_waitcnt vmcnt(12)
	s_barrier
	s_add_i32 m0, s7, 114688
	s_nop 0
	global_load_lds_dwordx4 v[180:181], off
	v_lshl_add_u64 v[180:181], v[180:181], 0, s[98:99]
	s_add_i32 m0, s7, 122880
	s_nop 0
	global_load_lds_dwordx4 v[180:181], off
	v_lshl_add_u64 v[180:181], v[180:181], 0, s[98:99]
	ds_read_b128 v[104:107], v178 offset:0
	ds_read_b128 v[146:149], v178 offset:8192
	ds_read_b128 v[108:111], v178 offset:1024
	ds_read_b128 v[150:153], v178 offset:9216
	ds_read_b128 v[112:115], v178 offset:2048
	ds_read_b128 v[154:157], v178 offset:10240
	ds_read_b128 v[116:119], v178 offset:3072
	ds_read_b128 v[158:161], v178 offset:11264
	ds_read_b128 v[120:123], v178 offset:4096
	ds_read_b128 v[162:165], v178 offset:12288
	ds_read_b128 v[124:127], v178 offset:5120
	ds_read_b128 v[166:169], v178 offset:13312
	ds_read_b128 v[128:131], v178 offset:6144
	ds_read_b128 v[170:173], v178 offset:14336
	ds_read_b128 v[132:135], v178 offset:7168
	ds_read_b128 v[174:177], v178 offset:15360
	s_setprio 1
	s_waitcnt lgkmcnt(14)
	v_mfma_f32_16x16x32_bf16 v[32:35], v[104:107], v[0:3], 0
	v_mfma_f32_16x16x32_bf16 v[36:39], v[146:149], v[0:3], 0
	s_waitcnt lgkmcnt(12)
	v_mfma_f32_16x16x32_bf16 v[32:35], v[108:111], v[4:7], v[32:35]
	v_mfma_f32_16x16x32_bf16 v[36:39], v[150:153], v[4:7], v[36:39]
	s_waitcnt lgkmcnt(10)
	v_mfma_f32_16x16x32_bf16 v[32:35], v[112:115], v[8:11], v[32:35]
	v_mfma_f32_16x16x32_bf16 v[36:39], v[154:157], v[8:11], v[36:39]
	s_waitcnt lgkmcnt(8)
	v_mfma_f32_16x16x32_bf16 v[32:35], v[116:119], v[12:15], v[32:35]
	v_mfma_f32_16x16x32_bf16 v[36:39], v[158:161], v[12:15], v[36:39]
	s_waitcnt lgkmcnt(6)
	v_mfma_f32_16x16x32_bf16 v[32:35], v[120:123], v[16:19], v[32:35]
	v_mfma_f32_16x16x32_bf16 v[36:39], v[162:165], v[16:19], v[36:39]
	s_waitcnt lgkmcnt(4)
	v_mfma_f32_16x16x32_bf16 v[32:35], v[124:127], v[20:23], v[32:35]
	v_mfma_f32_16x16x32_bf16 v[36:39], v[166:169], v[20:23], v[36:39]
	s_waitcnt lgkmcnt(2)
	v_mfma_f32_16x16x32_bf16 v[32:35], v[128:131], v[24:27], v[32:35]
	v_mfma_f32_16x16x32_bf16 v[36:39], v[170:173], v[24:27], v[36:39]
	s_waitcnt lgkmcnt(0)
	v_mfma_f32_16x16x32_bf16 v[32:35], v[132:135], v[28:31], v[32:35]
	v_mfma_f32_16x16x32_bf16 v[36:39], v[174:177], v[28:31], v[36:39]
	s_setprio 0
	s_waitcnt vmcnt(12)
	s_barrier
; __device__ __forceinline__ f32x4 mfma16(bf16x8 a, bf16x8 b, f32x4 c) { return __builtin_amdgcn_mfma_f32_16x16x32_bf16(a, b, c, 0, 0, 0); }
; __device__ __forceinline__ void mem_task(bf16_t* zb, const bf16_t* kvm_b, const bf16_t* vmt_b, int hm, int t0, int lane, bool do_store) {
;     ...
;     for (int kt = 0; kt < 16; ++kt) {
;         if (kt + 2 < 16) { const bf16_t* kp = kbase + (size_t)(((kt + 2) >> 1) * 32 + 4 * ((kt + 2) & 1)) * 2048;
; #pragma unroll
;             for (int kk = 0; kk < 8; ++kk) kfr[(kt + 2) % 3][kk] = *(const bf16x8*)(kp + kk * 32); }
;         f32x4 acc = zero4;
;         __builtin_amdgcn_s_setprio(1);
; #pragma unroll
;         for (int kk = 0; kk < 8; ++kk) acc = mfma16(kfr[kt % 3][kk], qf[kk], acc);
;         __builtin_amdgcn_s_setprio(0);
;         s[kt] = acc; }
	s_add_i32 m0, s7, 0
	s_nop 0
	global_load_lds_dwordx4 v[182:183], off
	v_lshl_add_u64 v[182:183], v[182:183], 0, s[98:99]
	s_add_i32 m0, s7, 8192
	s_nop 0
	global_load_lds_dwordx4 v[182:183], off
	v_lshl_add_u64 v[182:183], v[182:183], 0, s[98:99]
	ds_read_b128 v[104:107], v178 offset:16384
	ds_read_b128 v[146:149], v178 offset:24576
	ds_read_b128 v[108:111], v178 offset:17408
	ds_read_b128 v[150:153], v178 offset:25600
	ds_read_b128 v[112:115], v178 offset:18432
	ds_read_b128 v[154:157], v178 offset:26624
	ds_read_b128 v[116:119], v178 offset:19456
	ds_read_b128 v[158:161], v178 offset:27648
	ds_read_b128 v[120:123], v178 offset:20480
	ds_read_b128 v[162:165], v178 offset:28672
	ds_read_b128 v[124:127], v178 offset:21504
	ds_read_b128 v[166:169], v178 offset:29696
	ds_read_b128 v[128:131], v178 offset:22528
	ds_read_b128 v[170:173], v178 offset:30720
	ds_read_b128 v[132:135], v178 offset:23552
	ds_read_b128 v[174:177], v178 offset:31744
	s_setprio 1
	s_waitcnt lgkmcnt(14)
	v_mfma_f32_16x16x32_bf16 v[40:43], v[104:107], v[0:3], 0
	v_mfma_f32_16x16x32_bf16 v[44:47], v[146:149], v[0:3], 0
	s_waitcnt lgkmcnt(12)
	v_mfma_f32_16x16x32_bf16 v[40:43], v[108:111], v[4:7], v[40:43]
	v_mfma_f32_16x16x32_bf16 v[44:47], v[150:153], v[4:7], v[44:47]
	s_waitcnt lgkmcnt(10)
	v_mfma_f32_16x16x32_bf16 v[40:43], v[112:115], v[8:11], v[40:43]
	v_mfma_f32_16x16x32_bf16 v[44:47], v[154:157], v[8:11], v[44:47]
	s_waitcnt lgkmcnt(8)
	v_mfma_f32_16x16x32_bf16 v[40:43], v[116:119], v[12:15], v[40:43]
	v_mfma_f32_16x16x32_bf16 v[44:47], v[158:161], v[12:15], v[44:47]
	s_waitcnt lgkmcnt(6)
	v_mfma_f32_16x16x32_bf16 v[40:43], v[120:123], v[16:19], v[40:43]
	v_mfma_f32_16x16x32_bf16 v[44:47], v[162:165], v[16:19], v[44:47]
	s_waitcnt lgkmcnt(4)
	v_mfma_f32_16x16x32_bf16 v[40:43], v[124:127], v[20:23], v[40:43]
	v_mfma_f32_16x16x32_bf16 v[44:47], v[166:169], v[20:23], v[44:47]
	s_waitcnt lgkmcnt(2)
	v_mfma_f32_16x16x32_bf16 v[40:43], v[128:131], v[24:27], v[40:43]
	v_mfma_f32_16x16x32_bf16 v[44:47], v[170:173], v[24:27], v[44:47]
	s_waitcnt lgkmcnt(0)
	v_mfma_f32_16x16x32_bf16 v[40:43], v[132:135], v[28:31], v[40:43]
	v_mfma_f32_16x16x32_bf16 v[44:47], v[174:177], v[28:31], v[44:47]
	s_setprio 0
	s_waitcnt vmcnt(12)
	s_barrier
	s_add_i32 m0, s7, 16384
	s_nop 0
	global_load_lds_dwordx4 v[182:183], off
	v_lshl_add_u64 v[182:183], v[182:183], 0, s[98:99]
	s_add_i32 m0, s7, 24576
	s_nop 0
	global_load_lds_dwordx4 v[182:183], off
	v_lshl_add_u64 v[182:183], v[182:183], 0, s[98:99]
	ds_read_b128 v[104:107], v178 offset:32768
	ds_read_b128 v[146:149], v178 offset:40960
	ds_read_b128 v[108:111], v178 offset:33792
	ds_read_b128 v[150:153], v178 offset:41984
	ds_read_b128 v[112:115], v178 offset:34816
	ds_read_b128 v[154:157], v178 offset:43008
	ds_read_b128 v[116:119], v178 offset:35840
	ds_read_b128 v[158:161], v178 offset:44032
	ds_read_b128 v[120:123], v178 offset:36864
	ds_read_b128 v[162:165], v178 offset:45056
	ds_read_b128 v[124:127], v178 offset:37888
	ds_read_b128 v[166:169], v178 offset:46080
	ds_read_b128 v[128:131], v178 offset:38912
	ds_read_b128 v[170:173], v178 offset:47104
	ds_read_b128 v[132:135], v178 offset:39936
	ds_read_b128 v[174:177], v178 offset:48128
	s_setprio 1
	s_waitcnt lgkmcnt(14)
	v_mfma_f32_16x16x32_bf16 v[48:51], v[104:107], v[0:3], 0
	v_mfma_f32_16x16x32_bf16 v[52:55], v[146:149], v[0:3], 0
	s_waitcnt lgkmcnt(12)
	v_mfma_f32_16x16x32_bf16 v[48:51], v[108:111], v[4:7], v[48:51]
	v_mfma_f32_16x16x32_bf16 v[52:55], v[150:153], v[4:7], v[52:55]
	s_waitcnt lgkmcnt(10)
	v_mfma_f32_16x16x32_bf16 v[48:51], v[112:115], v[8:11], v[48:51]
	v_mfma_f32_16x16x32_bf16 v[52:55], v[154:157], v[8:11], v[52:55]
	s_waitcnt lgkmcnt(8)
	v_mfma_f32_16x16x32_bf16 v[48:51], v[116:119], v[12:15], v[48:51]
	v_mfma_f32_16x16x32_bf16 v[52:55], v[158:161], v[12:15], v[52:55]
	s_waitcnt lgkmcnt(6)
	v_mfma_f32_16x16x32_bf16 v[48:51], v[120:123], v[16:19], v[48:51]
	v_mfma_f32_16x16x32_bf16 v[52:55], v[162:165], v[16:19], v[52:55]
	s_waitcnt lgkmcnt(4)
	v_mfma_f32_16x16x32_bf16 v[48:51], v[124:127], v[20:23], v[48:51]
	v_mfma_f32_16x16x32_bf16 v[52:55], v[166:169], v[20:23], v[52:55]
	s_waitcnt lgkmcnt(2)
	v_mfma_f32_16x16x32_bf16 v[48:51], v[128:131], v[24:27], v[48:51]
	v_mfma_f32_16x16x32_bf16 v[52:55], v[170:173], v[24:27], v[52:55]
	s_waitcnt lgkmcnt(0)
	v_mfma_f32_16x16x32_bf16 v[48:51], v[132:135], v[28:31], v[48:51]
	v_mfma_f32_16x16x32_bf16 v[52:55], v[174:177], v[28:31], v[52:55]
	s_setprio 0
	s_waitcnt vmcnt(12)
	s_barrier
	s_add_i32 m0, s7, 32768
	s_nop 0
	global_load_lds_dwordx4 v[182:183], off
	v_lshl_add_u64 v[182:183], v[182:183], 0, s[98:99]
	s_add_i32 m0, s7, 40960
	s_nop 0
	global_load_lds_dwordx4 v[182:183], off
	v_lshl_add_u64 v[182:183], v[182:183], 0, s[98:99]
	ds_read_b128 v[104:107], v178 offset:49152
	ds_read_b128 v[146:149], v178 offset:57344
	ds_read_b128 v[108:111], v178 offset:50176
	ds_read_b128 v[150:153], v178 offset:58368
	ds_read_b128 v[112:115], v178 offset:51200
	ds_read_b128 v[154:157], v178 offset:59392
	ds_read_b128 v[116:119], v178 offset:52224
	ds_read_b128 v[158:161], v178 offset:60416
	ds_read_b128 v[120:123], v178 offset:53248
	ds_read_b128 v[162:165], v178 offset:61440
	ds_read_b128 v[124:127], v178 offset:54272
	ds_read_b128 v[166:169], v178 offset:62464
	ds_read_b128 v[128:131], v178 offset:55296
	ds_read_b128 v[170:173], v178 offset:63488
	ds_read_b128 v[132:135], v178 offset:56320
	ds_read_b128 v[174:177], v178 offset:64512
	s_setprio 1
	s_waitcnt lgkmcnt(14)
	v_mfma_f32_16x16x32_bf16 v[56:59], v[104:107], v[0:3], 0
	v_mfma_f32_16x16x32_bf16 v[60:63], v[146:149], v[0:3], 0
	s_waitcnt lgkmcnt(12)
	v_mfma_f32_16x16x32_bf16 v[56:59], v[108:111], v[4:7], v[56:59]
	v_mfma_f32_16x16x32_bf16 v[60:63], v[150:153], v[4:7], v[60:63]
	s_waitcnt lgkmcnt(10)
	v_mfma_f32_16x16x32_bf16 v[56:59], v[112:115], v[8:11], v[56:59]
	v_mfma_f32_16x16x32_bf16 v[60:63], v[154:157], v[8:11], v[60:63]
	s_waitcnt lgkmcnt(8)
	v_mfma_f32_16x16x32_bf16 v[56:59], v[116:119], v[12:15], v[56:59]
	v_mfma_f32_16x16x32_bf16 v[60:63], v[158:161], v[12:15], v[60:63]
	s_waitcnt lgkmcnt(6)
	v_mfma_f32_16x16x32_bf16 v[56:59], v[120:123], v[16:19], v[56:59]
	v_mfma_f32_16x16x32_bf16 v[60:63], v[162:165], v[16:19], v[60:63]
	s_waitcnt lgkmcnt(4)
	v_mfma_f32_16x16x32_bf16 v[56:59], v[124:127], v[20:23], v[56:59]
	v_mfma_f32_16x16x32_bf16 v[60:63], v[166:169], v[20:23], v[60:63]
	s_waitcnt lgkmcnt(2)
	v_mfma_f32_16x16x32_bf16 v[56:59], v[128:131], v[24:27], v[56:59]
	v_mfma_f32_16x16x32_bf16 v[60:63], v[170:173], v[24:27], v[60:63]
	s_waitcnt lgkmcnt(0)
	v_mfma_f32_16x16x32_bf16 v[56:59], v[132:135], v[28:31], v[56:59]
	v_mfma_f32_16x16x32_bf16 v[60:63], v[174:177], v[28:31], v[60:63]
	s_setprio 0
	s_waitcnt vmcnt(12)
	s_barrier
; __device__ __forceinline__ f32x4 mfma16(bf16x8 a, bf16x8 b, f32x4 c) { return __builtin_amdgcn_mfma_f32_16x16x32_bf16(a, b, c, 0, 0, 0); }
; __device__ __forceinline__ void mem_task(bf16_t* zb, const bf16_t* kvm_b, const bf16_t* vmt_b, int hm, int t0, int lane, bool do_store) {
;     ...
;     for (int kt = 0; kt < 16; ++kt) {
;         if (kt + 2 < 16) { const bf16_t* kp = kbase + (size_t)(((kt + 2) >> 1) * 32 + 4 * ((kt + 2) & 1)) * 2048;
; #pragma unroll
;             for (int kk = 0; kk < 8; ++kk) kfr[(kt + 2) % 3][kk] = *(const bf16x8*)(kp + kk * 32); }
;         f32x4 acc = zero4;
;         __builtin_amdgcn_s_setprio(1);
; #pragma unroll
;         for (int kk = 0; kk < 8; ++kk) acc = mfma16(kfr[kt % 3][kk], qf[kk], acc);
;         __builtin_amdgcn_s_setprio(0);
;         s[kt] = acc; }
	s_add_i32 m0, s7, 49152
	s_nop 0
	global_load_lds_dwordx4 v[182:183], off
	v_lshl_add_u64 v[182:183], v[182:183], 0, s[98:99]
	s_add_i32 m0, s7, 57344
	s_nop 0
	global_load_lds_dwordx4 v[182:183], off
	v_lshl_add_u64 v[182:183], v[182:183], 0, s[98:99]
	ds_read_b128 v[104:107], v179 offset:0
	ds_read_b128 v[146:149], v179 offset:8192
	ds_read_b128 v[108:111], v179 offset:1024
	ds_read_b128 v[150:153], v179 offset:9216
	ds_read_b128 v[112:115], v179 offset:2048
	ds_read_b128 v[154:157], v179 offset:10240
	ds_read_b128 v[116:119], v179 offset:3072
	ds_read_b128 v[158:161], v179 offset:11264
	ds_read_b128 v[120:123], v179 offset:4096
	ds_read_b128 v[162:165], v179 offset:12288
	ds_read_b128 v[124:127], v179 offset:5120
	ds_read_b128 v[166:169], v179 offset:13312
	ds_read_b128 v[128:131], v179 offset:6144
	ds_read_b128 v[170:173], v179 offset:14336
	ds_read_b128 v[132:135], v179 offset:7168
	ds_read_b128 v[174:177], v179 offset:15360
	s_setprio 1
	s_waitcnt lgkmcnt(14)
	v_mfma_f32_16x16x32_bf16 v[72:75], v[104:107], v[0:3], 0
	v_mfma_f32_16x16x32_bf16 v[76:79], v[146:149], v[0:3], 0
	s_waitcnt lgkmcnt(12)
	v_mfma_f32_16x16x32_bf16 v[72:75], v[108:111], v[4:7], v[72:75]
	v_mfma_f32_16x16x32_bf16 v[76:79], v[150:153], v[4:7], v[76:79]
	s_waitcnt lgkmcnt(10)
	v_mfma_f32_16x16x32_bf16 v[72:75], v[112:115], v[8:11], v[72:75]
	v_mfma_f32_16x16x32_bf16 v[76:79], v[154:157], v[8:11], v[76:79]
	s_waitcnt lgkmcnt(8)
	v_mfma_f32_16x16x32_bf16 v[72:75], v[116:119], v[12:15], v[72:75]
	v_mfma_f32_16x16x32_bf16 v[76:79], v[158:161], v[12:15], v[76:79]
	s_waitcnt lgkmcnt(6)
	v_mfma_f32_16x16x32_bf16 v[72:75], v[120:123], v[16:19], v[72:75]
	v_mfma_f32_16x16x32_bf16 v[76:79], v[162:165], v[16:19], v[76:79]
	s_waitcnt lgkmcnt(4)
	v_mfma_f32_16x16x32_bf16 v[72:75], v[124:127], v[20:23], v[72:75]
	v_mfma_f32_16x16x32_bf16 v[76:79], v[166:169], v[20:23], v[76:79]
	s_waitcnt lgkmcnt(2)
	v_mfma_f32_16x16x32_bf16 v[72:75], v[128:131], v[24:27], v[72:75]
	v_mfma_f32_16x16x32_bf16 v[76:79], v[170:173], v[24:27], v[76:79]
	s_waitcnt lgkmcnt(0)
	v_mfma_f32_16x16x32_bf16 v[72:75], v[132:135], v[28:31], v[72:75]
	v_mfma_f32_16x16x32_bf16 v[76:79], v[174:177], v[28:31], v[76:79]
	s_setprio 0
	s_waitcnt vmcnt(12)
	s_barrier
	s_add_i32 m0, s7, 65536
	s_nop 0
	global_load_lds_dwordx4 v[182:183], off
	v_lshl_add_u64 v[182:183], v[182:183], 0, s[98:99]
	s_add_i32 m0, s7, 73728
	s_nop 0
	global_load_lds_dwordx4 v[182:183], off
	v_lshl_add_u64 v[182:183], v[182:183], 0, s[98:99]
	ds_read_b128 v[104:107], v179 offset:16384
	ds_read_b128 v[146:149], v179 offset:24576
	ds_read_b128 v[108:111], v179 offset:17408
	ds_read_b128 v[150:153], v179 offset:25600
	ds_read_b128 v[112:115], v179 offset:18432
	ds_read_b128 v[154:157], v179 offset:26624
	ds_read_b128 v[116:119], v179 offset:19456
	ds_read_b128 v[158:161], v179 offset:27648
	ds_read_b128 v[120:123], v179 offset:20480
	ds_read_b128 v[162:165], v179 offset:28672
	ds_read_b128 v[124:127], v179 offset:21504
	ds_read_b128 v[166:169], v179 offset:29696
	ds_read_b128 v[128:131], v179 offset:22528
	ds_read_b128 v[170:173], v179 offset:30720
	ds_read_b128 v[132:135], v179 offset:23552
	ds_read_b128 v[174:177], v179 offset:31744
	s_setprio 1
	s_waitcnt lgkmcnt(14)
	v_mfma_f32_16x16x32_bf16 v[80:83], v[104:107], v[0:3], 0
	v_mfma_f32_16x16x32_bf16 v[84:87], v[146:149], v[0:3], 0
	s_waitcnt lgkmcnt(12)
	v_mfma_f32_16x16x32_bf16 v[80:83], v[108:111], v[4:7], v[80:83]
	v_mfma_f32_16x16x32_bf16 v[84:87], v[150:153], v[4:7], v[84:87]
	s_waitcnt lgkmcnt(10)
	v_mfma_f32_16x16x32_bf16 v[80:83], v[112:115], v[8:11], v[80:83]
	v_mfma_f32_16x16x32_bf16 v[84:87], v[154:157], v[8:11], v[84:87]
	s_waitcnt lgkmcnt(8)
	v_mfma_f32_16x16x32_bf16 v[80:83], v[116:119], v[12:15], v[80:83]
	v_mfma_f32_16x16x32_bf16 v[84:87], v[158:161], v[12:15], v[84:87]
	s_waitcnt lgkmcnt(6)
	v_mfma_f32_16x16x32_bf16 v[80:83], v[120:123], v[16:19], v[80:83]
	v_mfma_f32_16x16x32_bf16 v[84:87], v[162:165], v[16:19], v[84:87]
	s_waitcnt lgkmcnt(4)
	v_mfma_f32_16x16x32_bf16 v[80:83], v[124:127], v[20:23], v[80:83]
	v_mfma_f32_16x16x32_bf16 v[84:87], v[166:169], v[20:23], v[84:87]
	s_waitcnt lgkmcnt(2)
	v_mfma_f32_16x16x32_bf16 v[80:83], v[128:131], v[24:27], v[80:83]
	v_mfma_f32_16x16x32_bf16 v[84:87], v[170:173], v[24:27], v[84:87]
	s_waitcnt lgkmcnt(0)
	v_mfma_f32_16x16x32_bf16 v[80:83], v[132:135], v[28:31], v[80:83]
	v_mfma_f32_16x16x32_bf16 v[84:87], v[174:177], v[28:31], v[84:87]
	s_setprio 0
	s_waitcnt vmcnt(12)
	s_barrier
	s_add_i32 m0, s7, 81920
	s_nop 0
	global_load_lds_dwordx4 v[182:183], off
	v_lshl_add_u64 v[182:183], v[182:183], 0, s[98:99]
	s_add_i32 m0, s7, 90112
	s_nop 0
	global_load_lds_dwordx4 v[182:183], off
	v_lshl_add_u64 v[182:183], v[182:183], 0, s[98:99]
	ds_read_b128 v[104:107], v179 offset:32768
	ds_read_b128 v[146:149], v179 offset:40960
	ds_read_b128 v[108:111], v179 offset:33792
	ds_read_b128 v[150:153], v179 offset:41984
	ds_read_b128 v[112:115], v179 offset:34816
	ds_read_b128 v[154:157], v179 offset:43008
	ds_read_b128 v[116:119], v179 offset:35840
	ds_read_b128 v[158:161], v179 offset:44032
	ds_read_b128 v[120:123], v179 offset:36864
	ds_read_b128 v[162:165], v179 offset:45056
	ds_read_b128 v[124:127], v179 offset:37888
	ds_read_b128 v[166:169], v179 offset:46080
	ds_read_b128 v[128:131], v179 offset:38912
	ds_read_b128 v[170:173], v179 offset:47104
	ds_read_b128 v[132:135], v179 offset:39936
	ds_read_b128 v[174:177], v179 offset:48128
	s_setprio 1
	s_waitcnt lgkmcnt(14)
	v_mfma_f32_16x16x32_bf16 v[88:91], v[104:107], v[0:3], 0
	v_mfma_f32_16x16x32_bf16 v[92:95], v[146:149], v[0:3], 0
	s_waitcnt lgkmcnt(12)
	v_mfma_f32_16x16x32_bf16 v[88:91], v[108:111], v[4:7], v[88:91]
	v_mfma_f32_16x16x32_bf16 v[92:95], v[150:153], v[4:7], v[92:95]
	s_waitcnt lgkmcnt(10)
	v_mfma_f32_16x16x32_bf16 v[88:91], v[112:115], v[8:11], v[88:91]
	v_mfma_f32_16x16x32_bf16 v[92:95], v[154:157], v[8:11], v[92:95]
	s_waitcnt lgkmcnt(8)
	v_mfma_f32_16x16x32_bf16 v[88:91], v[116:119], v[12:15], v[88:91]
	v_mfma_f32_16x16x32_bf16 v[92:95], v[158:161], v[12:15], v[92:95]
	s_waitcnt lgkmcnt(6)
	v_mfma_f32_16x16x32_bf16 v[88:91], v[120:123], v[16:19], v[88:91]
	v_mfma_f32_16x16x32_bf16 v[92:95], v[162:165], v[16:19], v[92:95]
	s_waitcnt lgkmcnt(4)
	v_mfma_f32_16x16x32_bf16 v[88:91], v[124:127], v[20:23], v[88:91]
	v_mfma_f32_16x16x32_bf16 v[92:95], v[166:169], v[20:23], v[92:95]
	s_waitcnt lgkmcnt(2)
	v_mfma_f32_16x16x32_bf16 v[88:91], v[128:131], v[24:27], v[88:91]
	v_mfma_f32_16x16x32_bf16 v[92:95], v[170:173], v[24:27], v[92:95]
	s_waitcnt lgkmcnt(0)
	v_mfma_f32_16x16x32_bf16 v[88:91], v[132:135], v[28:31], v[88:91]
	v_mfma_f32_16x16x32_bf16 v[92:95], v[174:177], v[28:31], v[92:95]
	s_setprio 0
	s_waitcnt vmcnt(12)
	s_barrier
; __device__ __forceinline__ f32x4 mfma16(bf16x8 a, bf16x8 b, f32x4 c) { return __builtin_amdgcn_mfma_f32_16x16x32_bf16(a, b, c, 0, 0, 0); }
; __device__ __forceinline__ void mem_task(bf16_t* zb, const bf16_t* kvm_b, const bf16_t* vmt_b, int hm, int t0, int lane, bool do_store) {
;     ...
;     for (int kt = 0; kt < 16; ++kt) {
;         if (kt + 2 < 16) { const bf16_t* kp = kbase + (size_t)(((kt + 2) >> 1) * 32 + 4 * ((kt + 2) & 1)) * 2048;
; #pragma unroll
;             for (int kk = 0; kk < 8; ++kk) kfr[(kt + 2) % 3][kk] = *(const bf16x8*)(kp + kk * 32); }
;         f32x4 acc = zero4;
;         __builtin_amdgcn_s_setprio(1);
; #pragma unroll
;         for (int kk = 0; kk < 8; ++kk) acc = mfma16(kfr[kt % 3][kk], qf[kk], acc);
;         __builtin_amdgcn_s_setprio(0);
;         s[kt] = acc; }
;     float l = 0.f;
; #pragma unroll
;     for (int kt = 0; kt < 16; ++kt)
; #pragma unroll
;         for (int j = 0; j < 4; ++j) { s[kt][j] = __builtin_amdgcn_exp2f(s[kt][j]); l += s[kt][j]; }
	s_add_i32 m0, s7, 98304
	s_nop 0
	global_load_lds_dwordx4 v[182:183], off
	v_lshl_add_u64 v[182:183], v[182:183], 0, s[98:99]
	s_add_i32 m0, s7, 106496
	s_nop 0
	global_load_lds_dwordx4 v[182:183], off
	v_lshl_add_u64 v[182:183], v[182:183], 0, s[98:99]
	ds_read_b128 v[104:107], v179 offset:49152
	ds_read_b128 v[146:149], v179 offset:57344
	ds_read_b128 v[108:111], v179 offset:50176
	ds_read_b128 v[150:153], v179 offset:58368
	ds_read_b128 v[112:115], v179 offset:51200
	ds_read_b128 v[154:157], v179 offset:59392
	ds_read_b128 v[116:119], v179 offset:52224
	ds_read_b128 v[158:161], v179 offset:60416
	ds_read_b128 v[120:123], v179 offset:53248
	ds_read_b128 v[162:165], v179 offset:61440
	ds_read_b128 v[124:127], v179 offset:54272
	ds_read_b128 v[166:169], v179 offset:62464
	ds_read_b128 v[128:131], v179 offset:55296
	ds_read_b128 v[170:173], v179 offset:63488
	ds_read_b128 v[132:135], v179 offset:56320
	ds_read_b128 v[174:177], v179 offset:64512
	s_setprio 1
	s_waitcnt lgkmcnt(14)
	v_mfma_f32_16x16x32_bf16 v[96:99], v[104:107], v[0:3], 0
	v_mfma_f32_16x16x32_bf16 v[100:103], v[146:149], v[0:3], 0
	s_waitcnt lgkmcnt(12)
	v_mfma_f32_16x16x32_bf16 v[96:99], v[108:111], v[4:7], v[96:99]
	v_mfma_f32_16x16x32_bf16 v[100:103], v[150:153], v[4:7], v[100:103]
	s_waitcnt lgkmcnt(10)
	v_mfma_f32_16x16x32_bf16 v[96:99], v[112:115], v[8:11], v[96:99]
	v_mfma_f32_16x16x32_bf16 v[100:103], v[154:157], v[8:11], v[100:103]
	s_waitcnt lgkmcnt(8)
	v_mfma_f32_16x16x32_bf16 v[96:99], v[116:119], v[12:15], v[96:99]
	v_mfma_f32_16x16x32_bf16 v[100:103], v[158:161], v[12:15], v[100:103]
	s_waitcnt lgkmcnt(6)
	v_mfma_f32_16x16x32_bf16 v[96:99], v[120:123], v[16:19], v[96:99]
	v_mfma_f32_16x16x32_bf16 v[100:103], v[162:165], v[16:19], v[100:103]
	s_waitcnt lgkmcnt(4)
	v_mfma_f32_16x16x32_bf16 v[96:99], v[124:127], v[20:23], v[96:99]
	v_mfma_f32_16x16x32_bf16 v[100:103], v[166:169], v[20:23], v[100:103]
	s_waitcnt lgkmcnt(2)
	v_mfma_f32_16x16x32_bf16 v[96:99], v[128:131], v[24:27], v[96:99]
	v_mfma_f32_16x16x32_bf16 v[100:103], v[170:173], v[24:27], v[100:103]
	s_waitcnt lgkmcnt(0)
	v_mfma_f32_16x16x32_bf16 v[96:99], v[132:135], v[28:31], v[96:99]
	v_mfma_f32_16x16x32_bf16 v[100:103], v[174:177], v[28:31], v[100:103]
	s_setprio 0
	s_nop 7
	s_nop 7
	v_exp_f32_e32 v32, v32
	v_exp_f32_e32 v33, v33
	v_add_f32_e32 v190, 0, v32
	v_exp_f32_e32 v34, v34
	v_add_f32_e32 v190, v190, v33
	v_exp_f32_e32 v35, v35
	v_add_f32_e32 v190, v190, v34
	v_exp_f32_e32 v36, v36
	v_add_f32_e32 v190, v190, v35
	v_exp_f32_e32 v37, v37
	v_add_f32_e32 v190, v190, v36
	v_exp_f32_e32 v38, v38
	v_add_f32_e32 v190, v190, v37
	v_exp_f32_e32 v39, v39
	v_add_f32_e32 v190, v190, v38
	v_exp_f32_e32 v40, v40
	v_add_f32_e32 v190, v190, v39
	v_exp_f32_e32 v41, v41
	v_add_f32_e32 v190, v190, v40
	v_exp_f32_e32 v42, v42
	v_add_f32_e32 v190, v190, v41
	v_exp_f32_e32 v43, v43
	v_add_f32_e32 v190, v190, v42
	v_exp_f32_e32 v44, v44
	v_add_f32_e32 v190, v190, v43
	v_exp_f32_e32 v45, v45
	v_add_f32_e32 v190, v190, v44
	v_exp_f32_e32 v46, v46
	v_add_f32_e32 v190, v190, v45
	v_exp_f32_e32 v47, v47
	v_add_f32_e32 v190, v190, v46
	v_exp_f32_e32 v48, v48
	v_add_f32_e32 v190, v190, v47
	v_exp_f32_e32 v49, v49
	v_add_f32_e32 v190, v190, v48
	v_exp_f32_e32 v50, v50
	v_add_f32_e32 v190, v190, v49
	v_exp_f32_e32 v51, v51
	v_add_f32_e32 v190, v190, v50
	v_exp_f32_e32 v52, v52
	v_add_f32_e32 v190, v190, v51
	v_exp_f32_e32 v53, v53
	v_add_f32_e32 v190, v190, v52
	v_exp_f32_e32 v54, v54
	v_add_f32_e32 v190, v190, v53
	v_exp_f32_e32 v55, v55
	v_add_f32_e32 v190, v190, v54
	v_exp_f32_e32 v56, v56
	v_add_f32_e32 v190, v190, v55
	v_exp_f32_e32 v57, v57
	v_add_f32_e32 v190, v190, v56
	v_exp_f32_e32 v58, v58
	v_add_f32_e32 v190, v190, v57
	v_exp_f32_e32 v59, v59
	v_add_f32_e32 v190, v190, v58
	v_exp_f32_e32 v60, v60
	v_add_f32_e32 v190, v190, v59
	v_exp_f32_e32 v61, v61
	v_add_f32_e32 v190, v190, v60
	v_exp_f32_e32 v62, v62
	v_add_f32_e32 v190, v190, v61
	v_exp_f32_e32 v63, v63
	v_add_f32_e32 v190, v190, v62
	v_exp_f32_e32 v72, v72
	v_add_f32_e32 v190, v190, v63
	v_exp_f32_e32 v73, v73
	v_add_f32_e32 v190, v190, v72
	v_exp_f32_e32 v74, v74
	v_add_f32_e32 v190, v190, v73
	v_exp_f32_e32 v75, v75
	v_add_f32_e32 v190, v190, v74
	v_exp_f32_e32 v76, v76
	v_add_f32_e32 v190, v190, v75
	v_exp_f32_e32 v77, v77
	v_add_f32_e32 v190, v190, v76
	v_exp_f32_e32 v78, v78
	v_add_f32_e32 v190, v190, v77
	v_exp_f32_e32 v79, v79
	v_add_f32_e32 v190, v190, v78
	v_exp_f32_e32 v80, v80
	v_add_f32_e32 v190, v190, v79
	v_exp_f32_e32 v81, v81
	v_add_f32_e32 v190, v190, v80
	v_exp_f32_e32 v82, v82
	v_add_f32_e32 v190, v190, v81
	v_exp_f32_e32 v83, v83
	v_add_f32_e32 v190, v190, v82
	v_exp_f32_e32 v84, v84
	v_add_f32_e32 v190, v190, v83
	v_exp_f32_e32 v85, v85
	v_add_f32_e32 v190, v190, v84
	v_exp_f32_e32 v86, v86
	v_add_f32_e32 v190, v190, v85
	v_exp_f32_e32 v87, v87
	v_add_f32_e32 v190, v190, v86
	v_exp_f32_e32 v88, v88
	v_add_f32_e32 v190, v190, v87
	v_exp_f32_e32 v89, v89
	v_add_f32_e32 v190, v190, v88
	v_exp_f32_e32 v90, v90
	v_add_f32_e32 v190, v190, v89
	v_exp_f32_e32 v91, v91
	v_add_f32_e32 v190, v190, v90
	v_exp_f32_e32 v92, v92
	v_add_f32_e32 v190, v190, v91
	v_exp_f32_e32 v93, v93
	v_add_f32_e32 v190, v190, v92
	v_exp_f32_e32 v94, v94
	v_add_f32_e32 v190, v190, v93
	v_exp_f32_e32 v95, v95
	v_add_f32_e32 v190, v190, v94
	v_exp_f32_e32 v96, v96
	v_add_f32_e32 v190, v190, v95
	v_exp_f32_e32 v97, v97
	v_add_f32_e32 v190, v190, v96
	v_exp_f32_e32 v98, v98
	v_add_f32_e32 v190, v190, v97
	v_exp_f32_e32 v99, v99
	v_add_f32_e32 v190, v190, v98
	v_exp_f32_e32 v100, v100
	v_add_f32_e32 v190, v190, v99
	v_exp_f32_e32 v101, v101
	v_add_f32_e32 v190, v190, v100
; __device__ __forceinline__ unsigned cvt_pk_bf16(float lo, float hi) { unsigned r; asm volatile("v_cvt_pk_bf16_f32 %0, %1, %2" : "=v"(r) : "v"(lo), "v"(hi)); return r; }
; __device__ __forceinline__ f32x4 mfma16(bf16x8 a, bf16x8 b, f32x4 c) { return __builtin_amdgcn_mfma_f32_16x16x32_bf16(a, b, c, 0, 0, 0); }
; __device__ __forceinline__ float x16sum(float x) { auto r = __builtin_amdgcn_permlane16_swap(__float_as_uint(x), __float_as_uint(x), false, false); return __uint_as_float(r[0]) + __uint_as_float(r[1]); }
; __device__ __forceinline__ float x32sum(float x) { auto r = __builtin_amdgcn_permlane32_swap(__float_as_uint(x), __float_as_uint(x), false, false); return __uint_as_float(r[0]) + __uint_as_float(r[1]); }
; __device__ __forceinline__ void mem_task(bf16_t* zb, const bf16_t* kvm_b, const bf16_t* vmt_b, int hm, int t0, int lane, bool do_store) {
;     ...
;         for (int j = 0; j < 4; ++j) { s[kt][j] = __builtin_amdgcn_exp2f(s[kt][j]); l += s[kt][j]; }
;     l = x16sum(l); l = x32sum(l);
;     const float il = 1.0f / l;
;     bf16x8 pf[8];
; #pragma unroll
;     for (int kp = 0; kp < 8; ++kp) { u32x4 w; w.x = cvt_pk_bf16(s[2 * kp][0], s[2 * kp][1]); w.y = cvt_pk_bf16(s[2 * kp][2], s[2 * kp][3]); w.z = cvt_pk_bf16(s[2 * kp + 1][0], s[2 * kp + 1][1]); w.w = cvt_pk_bf16(s[2 * kp + 1][2], s[2 * kp + 1][3]); pf[kp] = __builtin_bit_cast(bf16x8, w); }
;     const bf16_t* vbase = vmt_b + (size_t)(hm * 256 + n) * 256 + 8 * fq;
;     bf16x8 vfr[3][8];
; #pragma unroll
;     for (int kp = 0; kp < 8; ++kp) vfr[0][kp] = *(const bf16x8*)(vbase + kp * 32);
;     { const bf16_t* vp = vbase + (size_t)16 * 256;
; #pragma unroll
;       for (int kp = 0; kp < 8; ++kp) vfr[1][kp] = *(const bf16x8*)(vp + kp * 32); }
; #pragma unroll
;     for (int dt = 0; dt < 16; ++dt) {
;         if (dt + 2 < 16) { const bf16_t* vp = vbase + (size_t)((dt + 2) * 16) * 256;
; #pragma unroll
;             for (int kp = 0; kp < 8; ++kp) vfr[(dt + 2) % 3][kp] = *(const bf16x8*)(vp + kp * 32); }
;         f32x4 acc = zero4;
;         __builtin_amdgcn_s_setprio(1);
; #pragma unroll
;         for (int kp = 0; kp < 8; ++kp) acc = mfma16(vfr[dt % 3][kp], pf[kp], acc);
;         __builtin_amdgcn_s_setprio(0);
;         u32x2 w; w.x = cvt_pk_bf16(acc[0] * il, acc[1] * il); w.y = cvt_pk_bf16(acc[2] * il, acc[3] * il); if (do_store || acc[0] == 12345.678f) *(u32x2*)(qp + dt * 16 + 4 * fq) = w; }
	v_exp_f32_e32 v102, v102
	v_add_f32_e32 v190, v190, v101
	v_exp_f32_e32 v103, v103
	v_add_f32_e32 v190, v190, v102
	s_nop 0
	v_add_f32_e32 v190, v190, v103
	v_mov_b32_e32 v186, v190
	s_nop 1
	v_permlane16_swap_b32_e32 v190, v186
	v_add_f32_e32 v190, v190, v186
	v_mov_b32_e32 v186, v190
	s_nop 1
	v_permlane32_swap_b32_e32 v190, v186
	v_add_f32_e32 v190, v190, v186
	v_div_scale_f32 v186, s[12:13], v190, v190, 1.0
	v_rcp_f32_e32 v187, v186
	s_nop 0
	v_fma_f32 v188, -v186, v187, 1.0
	v_fmac_f32_e32 v187, v188, v187
	v_div_scale_f32 v188, vcc, 1.0, v190, 1.0
	v_mul_f32_e32 v189, v188, v187
	v_fma_f32 v136, -v186, v189, v188
	v_fmac_f32_e32 v189, v136, v187
	v_fma_f32 v186, -v186, v189, v188
	s_nop 0
	v_div_fmas_f32 v186, v186, v187, v189
	v_div_fixup_f32 v191, v186, v190, 1.0
	v_cvt_pk_bf16_f32 v32, v32, v33
	v_cvt_pk_bf16_f32 v33, v34, v35
	v_cvt_pk_bf16_f32 v34, v36, v37
	v_cvt_pk_bf16_f32 v35, v38, v39
	v_cvt_pk_bf16_f32 v40, v40, v41
	v_cvt_pk_bf16_f32 v41, v42, v43
	v_cvt_pk_bf16_f32 v42, v44, v45
	v_cvt_pk_bf16_f32 v43, v46, v47
	v_cvt_pk_bf16_f32 v48, v48, v49
	v_cvt_pk_bf16_f32 v49, v50, v51
	v_cvt_pk_bf16_f32 v50, v52, v53
	v_cvt_pk_bf16_f32 v51, v54, v55
	v_cvt_pk_bf16_f32 v56, v56, v57
	v_cvt_pk_bf16_f32 v57, v58, v59
	v_cvt_pk_bf16_f32 v58, v60, v61
	v_cvt_pk_bf16_f32 v59, v62, v63
	v_cvt_pk_bf16_f32 v72, v72, v73
	v_cvt_pk_bf16_f32 v73, v74, v75
	v_cvt_pk_bf16_f32 v74, v76, v77
	v_cvt_pk_bf16_f32 v75, v78, v79
	v_cvt_pk_bf16_f32 v80, v80, v81
	v_cvt_pk_bf16_f32 v81, v82, v83
	v_cvt_pk_bf16_f32 v82, v84, v85
	v_cvt_pk_bf16_f32 v83, v86, v87
	v_cvt_pk_bf16_f32 v88, v88, v89
	v_cvt_pk_bf16_f32 v89, v90, v91
	v_cvt_pk_bf16_f32 v90, v92, v93
	v_cvt_pk_bf16_f32 v91, v94, v95
	v_cvt_pk_bf16_f32 v96, v96, v97
	v_cvt_pk_bf16_f32 v97, v98, v99
	v_cvt_pk_bf16_f32 v98, v100, v101
	v_cvt_pk_bf16_f32 v99, v102, v103
	s_waitcnt vmcnt(12)
	s_barrier
	s_add_i32 m0, s7, 114688
	s_nop 0
	global_load_lds_dwordx4 v[182:183], off
	v_lshl_add_u64 v[182:183], v[182:183], 0, s[98:99]
	s_add_i32 m0, s7, 122880
	s_nop 0
	global_load_lds_dwordx4 v[182:183], off
	v_lshl_add_u64 v[182:183], v[182:183], 0, s[98:99]
	ds_read_b128 v[104:107], v178 offset:0
	ds_read_b128 v[146:149], v178 offset:8192
	ds_read_b128 v[108:111], v178 offset:1024
	ds_read_b128 v[150:153], v178 offset:9216
	ds_read_b128 v[112:115], v178 offset:2048
	ds_read_b128 v[154:157], v178 offset:10240
	ds_read_b128 v[116:119], v178 offset:3072
	ds_read_b128 v[158:161], v178 offset:11264
	ds_read_b128 v[120:123], v178 offset:4096
	ds_read_b128 v[162:165], v178 offset:12288
	ds_read_b128 v[124:127], v178 offset:5120
	ds_read_b128 v[166:169], v178 offset:13312
	ds_read_b128 v[128:131], v178 offset:6144
	ds_read_b128 v[170:173], v178 offset:14336
	ds_read_b128 v[132:135], v178 offset:7168
	ds_read_b128 v[174:177], v178 offset:15360
	s_setprio 1
	s_waitcnt lgkmcnt(14)
	v_mfma_f32_16x16x32_bf16 v[192:195], v[104:107], v[32:35], 0
	v_mfma_f32_16x16x32_bf16 v[196:199], v[146:149], v[32:35], 0
	s_waitcnt lgkmcnt(12)
	v_mfma_f32_16x16x32_bf16 v[192:195], v[108:111], v[40:43], v[192:195]
	v_mfma_f32_16x16x32_bf16 v[196:199], v[150:153], v[40:43], v[196:199]
	s_waitcnt lgkmcnt(10)
	v_mfma_f32_16x16x32_bf16 v[192:195], v[112:115], v[48:51], v[192:195]
	v_mfma_f32_16x16x32_bf16 v[196:199], v[154:157], v[48:51], v[196:199]
	s_waitcnt lgkmcnt(8)
	v_mfma_f32_16x16x32_bf16 v[192:195], v[116:119], v[56:59], v[192:195]
	v_mfma_f32_16x16x32_bf16 v[196:199], v[158:161], v[56:59], v[196:199]
	s_waitcnt lgkmcnt(6)
	v_mfma_f32_16x16x32_bf16 v[192:195], v[120:123], v[72:75], v[192:195]
	v_mfma_f32_16x16x32_bf16 v[196:199], v[162:165], v[72:75], v[196:199]
	s_waitcnt lgkmcnt(4)
	v_mfma_f32_16x16x32_bf16 v[192:195], v[124:127], v[80:83], v[192:195]
	v_mfma_f32_16x16x32_bf16 v[196:199], v[166:169], v[80:83], v[196:199]
	s_waitcnt lgkmcnt(2)
	v_mfma_f32_16x16x32_bf16 v[192:195], v[128:131], v[88:91], v[192:195]
	v_mfma_f32_16x16x32_bf16 v[196:199], v[170:173], v[88:91], v[196:199]
	s_waitcnt lgkmcnt(0)
	v_mfma_f32_16x16x32_bf16 v[192:195], v[132:135], v[96:99], v[192:195]
	v_mfma_f32_16x16x32_bf16 v[196:199], v[174:177], v[96:99], v[196:199]
	s_setprio 0
	s_waitcnt vmcnt(12)
	s_barrier
	ds_read_b128 v[104:107], v178 offset:16384
	ds_read_b128 v[146:149], v178 offset:24576
	ds_read_b128 v[108:111], v178 offset:17408
	ds_read_b128 v[150:153], v178 offset:25600
	ds_read_b128 v[112:115], v178 offset:18432
	ds_read_b128 v[154:157], v178 offset:26624
	ds_read_b128 v[116:119], v178 offset:19456
	ds_read_b128 v[158:161], v178 offset:27648
	ds_read_b128 v[120:123], v178 offset:20480
	ds_read_b128 v[162:165], v178 offset:28672
	ds_read_b128 v[124:127], v178 offset:21504
	ds_read_b128 v[166:169], v178 offset:29696
	ds_read_b128 v[128:131], v178 offset:22528
	ds_read_b128 v[170:173], v178 offset:30720
	ds_read_b128 v[132:135], v178 offset:23552
	ds_read_b128 v[174:177], v178 offset:31744
	s_setprio 1
	s_waitcnt lgkmcnt(14)
	v_mfma_f32_16x16x32_bf16 v[206:209], v[104:107], v[32:35], 0
	v_mfma_f32_16x16x32_bf16 v[210:213], v[146:149], v[32:35], 0
	s_waitcnt lgkmcnt(12)
	v_mfma_f32_16x16x32_bf16 v[206:209], v[108:111], v[40:43], v[206:209]
	v_mfma_f32_16x16x32_bf16 v[210:213], v[150:153], v[40:43], v[210:213]
	s_waitcnt lgkmcnt(10)
	v_mfma_f32_16x16x32_bf16 v[206:209], v[112:115], v[48:51], v[206:209]
	v_mfma_f32_16x16x32_bf16 v[210:213], v[154:157], v[48:51], v[210:213]
	s_waitcnt lgkmcnt(8)
	v_mfma_f32_16x16x32_bf16 v[206:209], v[116:119], v[56:59], v[206:209]
	v_mfma_f32_16x16x32_bf16 v[210:213], v[158:161], v[56:59], v[210:213]
	s_waitcnt lgkmcnt(6)
	v_mfma_f32_16x16x32_bf16 v[206:209], v[120:123], v[72:75], v[206:209]
	v_mfma_f32_16x16x32_bf16 v[210:213], v[162:165], v[72:75], v[210:213]
	s_waitcnt lgkmcnt(4)
	v_mfma_f32_16x16x32_bf16 v[206:209], v[124:127], v[80:83], v[206:209]
	v_mfma_f32_16x16x32_bf16 v[210:213], v[166:169], v[80:83], v[210:213]
	s_waitcnt lgkmcnt(2)
	v_mfma_f32_16x16x32_bf16 v[206:209], v[128:131], v[88:91], v[206:209]
	v_mfma_f32_16x16x32_bf16 v[210:213], v[170:173], v[88:91], v[210:213]
	s_waitcnt lgkmcnt(0)
	v_mfma_f32_16x16x32_bf16 v[206:209], v[132:135], v[96:99], v[206:209]
	v_mfma_f32_16x16x32_bf16 v[210:213], v[174:177], v[96:99], v[210:213]
	s_setprio 0
	v_mul_f32_e32 v192, v191, v192
	v_mul_f32_e32 v193, v191, v193
	v_mul_f32_e32 v194, v191, v194
	v_mul_f32_e32 v195, v191, v195
	v_cvt_pk_bf16_f32 v192, v192, v193
	v_cvt_pk_bf16_f32 v193, v194, v195
	global_store_dwordx2 v[184:185], v[192:193], off
	v_mul_f32_e32 v196, v191, v196
	v_mul_f32_e32 v197, v191, v197
	v_mul_f32_e32 v198, v191, v198
	v_mul_f32_e32 v199, v191, v199
	v_cvt_pk_bf16_f32 v196, v196, v197
	v_cvt_pk_bf16_f32 v197, v198, v199
	global_store_dwordx2 v[184:185], v[196:197], off offset:32
	s_waitcnt vmcnt(12)
	s_barrier
; __device__ __forceinline__ unsigned cvt_pk_bf16(float lo, float hi) { unsigned r; asm volatile("v_cvt_pk_bf16_f32 %0, %1, %2" : "=v"(r) : "v"(lo), "v"(hi)); return r; }
; __device__ __forceinline__ f32x4 mfma16(bf16x8 a, bf16x8 b, f32x4 c) { return __builtin_amdgcn_mfma_f32_16x16x32_bf16(a, b, c, 0, 0, 0); }
; __device__ __forceinline__ void mem_task(bf16_t* zb, const bf16_t* kvm_b, const bf16_t* vmt_b, int hm, int t0, int lane, bool do_store) {
;     ...
; #pragma unroll
;     for (int dt = 0; dt < 16; ++dt) {
;         if (dt + 2 < 16) { const bf16_t* vp = vbase + (size_t)((dt + 2) * 16) * 256;
; #pragma unroll
;             for (int kp = 0; kp < 8; ++kp) vfr[(dt + 2) % 3][kp] = *(const bf16x8*)(vp + kp * 32); }
;         f32x4 acc = zero4;
;         __builtin_amdgcn_s_setprio(1);
; #pragma unroll
;         for (int kp = 0; kp < 8; ++kp) acc = mfma16(vfr[dt % 3][kp], pf[kp], acc);
;         __builtin_amdgcn_s_setprio(0);
;         u32x2 w; w.x = cvt_pk_bf16(acc[0] * il, acc[1] * il); w.y = cvt_pk_bf16(acc[2] * il, acc[3] * il); if (do_store || acc[0] == 12345.678f) *(u32x2*)(qp + dt * 16 + 4 * fq) = w; }
	ds_read_b128 v[104:107], v178 offset:32768
	ds_read_b128 v[146:149], v178 offset:40960
	ds_read_b128 v[108:111], v178 offset:33792
	ds_read_b128 v[150:153], v178 offset:41984
	ds_read_b128 v[112:115], v178 offset:34816
	ds_read_b128 v[154:157], v178 offset:43008
	ds_read_b128 v[116:119], v178 offset:35840
	ds_read_b128 v[158:161], v178 offset:44032
	ds_read_b128 v[120:123], v178 offset:36864
	ds_read_b128 v[162:165], v178 offset:45056
	ds_read_b128 v[124:127], v178 offset:37888
	ds_read_b128 v[166:169], v178 offset:46080
	ds_read_b128 v[128:131], v178 offset:38912
	ds_read_b128 v[170:173], v178 offset:47104
	ds_read_b128 v[132:135], v178 offset:39936
	ds_read_b128 v[174:177], v178 offset:48128
	s_setprio 1
	s_waitcnt lgkmcnt(14)
	v_mfma_f32_16x16x32_bf16 v[192:195], v[104:107], v[32:35], 0
	v_mfma_f32_16x16x32_bf16 v[196:199], v[146:149], v[32:35], 0
	s_waitcnt lgkmcnt(12)
	v_mfma_f32_16x16x32_bf16 v[192:195], v[108:111], v[40:43], v[192:195]
	v_mfma_f32_16x16x32_bf16 v[196:199], v[150:153], v[40:43], v[196:199]
	s_waitcnt lgkmcnt(10)
	v_mfma_f32_16x16x32_bf16 v[192:195], v[112:115], v[48:51], v[192:195]
	v_mfma_f32_16x16x32_bf16 v[196:199], v[154:157], v[48:51], v[196:199]
	s_waitcnt lgkmcnt(8)
	v_mfma_f32_16x16x32_bf16 v[192:195], v[116:119], v[56:59], v[192:195]
	v_mfma_f32_16x16x32_bf16 v[196:199], v[158:161], v[56:59], v[196:199]
	s_waitcnt lgkmcnt(6)
	v_mfma_f32_16x16x32_bf16 v[192:195], v[120:123], v[72:75], v[192:195]
	v_mfma_f32_16x16x32_bf16 v[196:199], v[162:165], v[72:75], v[196:199]
	s_waitcnt lgkmcnt(4)
	v_mfma_f32_16x16x32_bf16 v[192:195], v[124:127], v[80:83], v[192:195]
	v_mfma_f32_16x16x32_bf16 v[196:199], v[166:169], v[80:83], v[196:199]
	s_waitcnt lgkmcnt(2)
	v_mfma_f32_16x16x32_bf16 v[192:195], v[128:131], v[88:91], v[192:195]
	v_mfma_f32_16x16x32_bf16 v[196:199], v[170:173], v[88:91], v[196:199]
	s_waitcnt lgkmcnt(0)
	v_mfma_f32_16x16x32_bf16 v[192:195], v[132:135], v[96:99], v[192:195]
	v_mfma_f32_16x16x32_bf16 v[196:199], v[174:177], v[96:99], v[196:199]
	s_setprio 0
	v_mul_f32_e32 v206, v191, v206
	v_mul_f32_e32 v207, v191, v207
	v_mul_f32_e32 v208, v191, v208
	v_mul_f32_e32 v209, v191, v209
	v_cvt_pk_bf16_f32 v206, v206, v207
	v_cvt_pk_bf16_f32 v207, v208, v209
	global_store_dwordx2 v[184:185], v[206:207], off offset:64
	v_mul_f32_e32 v210, v191, v210
	v_mul_f32_e32 v211, v191, v211
	v_mul_f32_e32 v212, v191, v212
	v_mul_f32_e32 v213, v191, v213
	v_cvt_pk_bf16_f32 v210, v210, v211
	v_cvt_pk_bf16_f32 v211, v212, v213
	global_store_dwordx2 v[184:185], v[210:211], off offset:96
	s_waitcnt vmcnt(12)
	s_barrier
	ds_read_b128 v[104:107], v178 offset:49152
	ds_read_b128 v[146:149], v178 offset:57344
	ds_read_b128 v[108:111], v178 offset:50176
	ds_read_b128 v[150:153], v178 offset:58368
	ds_read_b128 v[112:115], v178 offset:51200
	ds_read_b128 v[154:157], v178 offset:59392
	ds_read_b128 v[116:119], v178 offset:52224
	ds_read_b128 v[158:161], v178 offset:60416
	ds_read_b128 v[120:123], v178 offset:53248
	ds_read_b128 v[162:165], v178 offset:61440
	ds_read_b128 v[124:127], v178 offset:54272
	ds_read_b128 v[166:169], v178 offset:62464
	ds_read_b128 v[128:131], v178 offset:55296
	ds_read_b128 v[170:173], v178 offset:63488
	ds_read_b128 v[132:135], v178 offset:56320
	ds_read_b128 v[174:177], v178 offset:64512
	s_setprio 1
	s_waitcnt lgkmcnt(14)
	v_mfma_f32_16x16x32_bf16 v[206:209], v[104:107], v[32:35], 0
	v_mfma_f32_16x16x32_bf16 v[210:213], v[146:149], v[32:35], 0
	s_waitcnt lgkmcnt(12)
	v_mfma_f32_16x16x32_bf16 v[206:209], v[108:111], v[40:43], v[206:209]
	v_mfma_f32_16x16x32_bf16 v[210:213], v[150:153], v[40:43], v[210:213]
	s_waitcnt lgkmcnt(10)
	v_mfma_f32_16x16x32_bf16 v[206:209], v[112:115], v[48:51], v[206:209]
	v_mfma_f32_16x16x32_bf16 v[210:213], v[154:157], v[48:51], v[210:213]
	s_waitcnt lgkmcnt(8)
	v_mfma_f32_16x16x32_bf16 v[206:209], v[116:119], v[56:59], v[206:209]
	v_mfma_f32_16x16x32_bf16 v[210:213], v[158:161], v[56:59], v[210:213]
	s_waitcnt lgkmcnt(6)
	v_mfma_f32_16x16x32_bf16 v[206:209], v[120:123], v[72:75], v[206:209]
	v_mfma_f32_16x16x32_bf16 v[210:213], v[162:165], v[72:75], v[210:213]
	s_waitcnt lgkmcnt(4)
	v_mfma_f32_16x16x32_bf16 v[206:209], v[124:127], v[80:83], v[206:209]
	v_mfma_f32_16x16x32_bf16 v[210:213], v[166:169], v[80:83], v[210:213]
	s_waitcnt lgkmcnt(2)
	v_mfma_f32_16x16x32_bf16 v[206:209], v[128:131], v[88:91], v[206:209]
	v_mfma_f32_16x16x32_bf16 v[210:213], v[170:173], v[88:91], v[210:213]
	s_waitcnt lgkmcnt(0)
	v_mfma_f32_16x16x32_bf16 v[206:209], v[132:135], v[96:99], v[206:209]
	v_mfma_f32_16x16x32_bf16 v[210:213], v[174:177], v[96:99], v[210:213]
	s_setprio 0
	v_mul_f32_e32 v192, v191, v192
	v_mul_f32_e32 v193, v191, v193
	v_mul_f32_e32 v194, v191, v194
	v_mul_f32_e32 v195, v191, v195
	v_cvt_pk_bf16_f32 v192, v192, v193
	v_cvt_pk_bf16_f32 v193, v194, v195
	global_store_dwordx2 v[184:185], v[192:193], off offset:128
	v_mul_f32_e32 v196, v191, v196
	v_mul_f32_e32 v197, v191, v197
	v_mul_f32_e32 v198, v191, v198
	v_mul_f32_e32 v199, v191, v199
	v_cvt_pk_bf16_f32 v196, v196, v197
	v_cvt_pk_bf16_f32 v197, v198, v199
	global_store_dwordx2 v[184:185], v[196:197], off offset:160
	s_waitcnt vmcnt(12)
	s_barrier
; __device__ __forceinline__ unsigned cvt_pk_bf16(float lo, float hi) { unsigned r; asm volatile("v_cvt_pk_bf16_f32 %0, %1, %2" : "=v"(r) : "v"(lo), "v"(hi)); return r; }
; __device__ __forceinline__ f32x4 mfma16(bf16x8 a, bf16x8 b, f32x4 c) { return __builtin_amdgcn_mfma_f32_16x16x32_bf16(a, b, c, 0, 0, 0); }
; __device__ __forceinline__ void mem_task(bf16_t* zb, const bf16_t* kvm_b, const bf16_t* vmt_b, int hm, int t0, int lane, bool do_store) {
;     ...
; #pragma unroll
;     for (int dt = 0; dt < 16; ++dt) {
;         if (dt + 2 < 16) { const bf16_t* vp = vbase + (size_t)((dt + 2) * 16) * 256;
; #pragma unroll
;             for (int kp = 0; kp < 8; ++kp) vfr[(dt + 2) % 3][kp] = *(const bf16x8*)(vp + kp * 32); }
;         f32x4 acc = zero4;
;         __builtin_amdgcn_s_setprio(1);
; #pragma unroll
;         for (int kp = 0; kp < 8; ++kp) acc = mfma16(vfr[dt % 3][kp], pf[kp], acc);
;         __builtin_amdgcn_s_setprio(0);
;         u32x2 w; w.x = cvt_pk_bf16(acc[0] * il, acc[1] * il); w.y = cvt_pk_bf16(acc[2] * il, acc[3] * il); if (do_store || acc[0] == 12345.678f) *(u32x2*)(qp + dt * 16 + 4 * fq) = w; }
	ds_read_b128 v[104:107], v179 offset:0
	ds_read_b128 v[146:149], v179 offset:8192
	ds_read_b128 v[108:111], v179 offset:1024
	ds_read_b128 v[150:153], v179 offset:9216
	ds_read_b128 v[112:115], v179 offset:2048
	ds_read_b128 v[154:157], v179 offset:10240
	ds_read_b128 v[116:119], v179 offset:3072
	ds_read_b128 v[158:161], v179 offset:11264
	ds_read_b128 v[120:123], v179 offset:4096
	ds_read_b128 v[162:165], v179 offset:12288
	ds_read_b128 v[124:127], v179 offset:5120
	ds_read_b128 v[166:169], v179 offset:13312
	ds_read_b128 v[128:131], v179 offset:6144
	ds_read_b128 v[170:173], v179 offset:14336
	ds_read_b128 v[132:135], v179 offset:7168
	ds_read_b128 v[174:177], v179 offset:15360
	s_setprio 1
	s_waitcnt lgkmcnt(14)
	v_mfma_f32_16x16x32_bf16 v[192:195], v[104:107], v[32:35], 0
	v_mfma_f32_16x16x32_bf16 v[196:199], v[146:149], v[32:35], 0
	s_waitcnt lgkmcnt(12)
	v_mfma_f32_16x16x32_bf16 v[192:195], v[108:111], v[40:43], v[192:195]
	v_mfma_f32_16x16x32_bf16 v[196:199], v[150:153], v[40:43], v[196:199]
	s_waitcnt lgkmcnt(10)
	v_mfma_f32_16x16x32_bf16 v[192:195], v[112:115], v[48:51], v[192:195]
	v_mfma_f32_16x16x32_bf16 v[196:199], v[154:157], v[48:51], v[196:199]
	s_waitcnt lgkmcnt(8)
	v_mfma_f32_16x16x32_bf16 v[192:195], v[116:119], v[56:59], v[192:195]
	v_mfma_f32_16x16x32_bf16 v[196:199], v[158:161], v[56:59], v[196:199]
	s_waitcnt lgkmcnt(6)
	v_mfma_f32_16x16x32_bf16 v[192:195], v[120:123], v[72:75], v[192:195]
	v_mfma_f32_16x16x32_bf16 v[196:199], v[162:165], v[72:75], v[196:199]
	s_waitcnt lgkmcnt(4)
	v_mfma_f32_16x16x32_bf16 v[192:195], v[124:127], v[80:83], v[192:195]
	v_mfma_f32_16x16x32_bf16 v[196:199], v[166:169], v[80:83], v[196:199]
	s_waitcnt lgkmcnt(2)
	v_mfma_f32_16x16x32_bf16 v[192:195], v[128:131], v[88:91], v[192:195]
	v_mfma_f32_16x16x32_bf16 v[196:199], v[170:173], v[88:91], v[196:199]
	s_waitcnt lgkmcnt(0)
	v_mfma_f32_16x16x32_bf16 v[192:195], v[132:135], v[96:99], v[192:195]
	v_mfma_f32_16x16x32_bf16 v[196:199], v[174:177], v[96:99], v[196:199]
	s_setprio 0
	v_mul_f32_e32 v206, v191, v206
	v_mul_f32_e32 v207, v191, v207
	v_mul_f32_e32 v208, v191, v208
	v_mul_f32_e32 v209, v191, v209
	v_cvt_pk_bf16_f32 v206, v206, v207
	v_cvt_pk_bf16_f32 v207, v208, v209
	global_store_dwordx2 v[184:185], v[206:207], off offset:192
	v_mul_f32_e32 v210, v191, v210
	v_mul_f32_e32 v211, v191, v211
	v_mul_f32_e32 v212, v191, v212
	v_mul_f32_e32 v213, v191, v213
	v_cvt_pk_bf16_f32 v210, v210, v211
	v_cvt_pk_bf16_f32 v211, v212, v213
	global_store_dwordx2 v[184:185], v[210:211], off offset:224
	s_waitcnt vmcnt(12)
	s_barrier
	ds_read_b128 v[104:107], v179 offset:16384
	ds_read_b128 v[146:149], v179 offset:24576
	ds_read_b128 v[108:111], v179 offset:17408
	ds_read_b128 v[150:153], v179 offset:25600
	ds_read_b128 v[112:115], v179 offset:18432
	ds_read_b128 v[154:157], v179 offset:26624
	ds_read_b128 v[116:119], v179 offset:19456
	ds_read_b128 v[158:161], v179 offset:27648
	ds_read_b128 v[120:123], v179 offset:20480
	ds_read_b128 v[162:165], v179 offset:28672
	ds_read_b128 v[124:127], v179 offset:21504
	ds_read_b128 v[166:169], v179 offset:29696
	ds_read_b128 v[128:131], v179 offset:22528
	ds_read_b128 v[170:173], v179 offset:30720
	ds_read_b128 v[132:135], v179 offset:23552
	ds_read_b128 v[174:177], v179 offset:31744
	s_setprio 1
	s_waitcnt lgkmcnt(14)
	v_mfma_f32_16x16x32_bf16 v[206:209], v[104:107], v[32:35], 0
	v_mfma_f32_16x16x32_bf16 v[210:213], v[146:149], v[32:35], 0
	s_waitcnt lgkmcnt(12)
	v_mfma_f32_16x16x32_bf16 v[206:209], v[108:111], v[40:43], v[206:209]
	v_mfma_f32_16x16x32_bf16 v[210:213], v[150:153], v[40:43], v[210:213]
	s_waitcnt lgkmcnt(10)
	v_mfma_f32_16x16x32_bf16 v[206:209], v[112:115], v[48:51], v[206:209]
	v_mfma_f32_16x16x32_bf16 v[210:213], v[154:157], v[48:51], v[210:213]
	s_waitcnt lgkmcnt(8)
	v_mfma_f32_16x16x32_bf16 v[206:209], v[116:119], v[56:59], v[206:209]
	v_mfma_f32_16x16x32_bf16 v[210:213], v[158:161], v[56:59], v[210:213]
	s_waitcnt lgkmcnt(6)
	v_mfma_f32_16x16x32_bf16 v[206:209], v[120:123], v[72:75], v[206:209]
	v_mfma_f32_16x16x32_bf16 v[210:213], v[162:165], v[72:75], v[210:213]
	s_waitcnt lgkmcnt(4)
	v_mfma_f32_16x16x32_bf16 v[206:209], v[124:127], v[80:83], v[206:209]
	v_mfma_f32_16x16x32_bf16 v[210:213], v[166:169], v[80:83], v[210:213]
	s_waitcnt lgkmcnt(2)
	v_mfma_f32_16x16x32_bf16 v[206:209], v[128:131], v[88:91], v[206:209]
	v_mfma_f32_16x16x32_bf16 v[210:213], v[170:173], v[88:91], v[210:213]
	s_waitcnt lgkmcnt(0)
	v_mfma_f32_16x16x32_bf16 v[206:209], v[132:135], v[96:99], v[206:209]
	v_mfma_f32_16x16x32_bf16 v[210:213], v[174:177], v[96:99], v[210:213]
	s_setprio 0
	v_mul_f32_e32 v192, v191, v192
	v_mul_f32_e32 v193, v191, v193
	v_mul_f32_e32 v194, v191, v194
	v_mul_f32_e32 v195, v191, v195
	v_cvt_pk_bf16_f32 v192, v192, v193
	v_cvt_pk_bf16_f32 v193, v194, v195
	global_store_dwordx2 v[184:185], v[192:193], off offset:256
	v_mul_f32_e32 v196, v191, v196
	v_mul_f32_e32 v197, v191, v197
	v_mul_f32_e32 v198, v191, v198
	v_mul_f32_e32 v199, v191, v199
	v_cvt_pk_bf16_f32 v196, v196, v197
	v_cvt_pk_bf16_f32 v197, v198, v199
	global_store_dwordx2 v[184:185], v[196:197], off offset:288
	s_waitcnt vmcnt(12)
	s_barrier
; __device__ __forceinline__ unsigned cvt_pk_bf16(float lo, float hi) { unsigned r; asm volatile("v_cvt_pk_bf16_f32 %0, %1, %2" : "=v"(r) : "v"(lo), "v"(hi)); return r; }
; __device__ __forceinline__ f32x4 mfma16(bf16x8 a, bf16x8 b, f32x4 c) { return __builtin_amdgcn_mfma_f32_16x16x32_bf16(a, b, c, 0, 0, 0); }
; __device__ __forceinline__ void mem_task(bf16_t* zb, const bf16_t* kvm_b, const bf16_t* vmt_b, int hm, int t0, int lane, bool do_store) {
;     ...
; #pragma unroll
;     for (int dt = 0; dt < 16; ++dt) {
;         if (dt + 2 < 16) { const bf16_t* vp = vbase + (size_t)((dt + 2) * 16) * 256;
; #pragma unroll
;             for (int kp = 0; kp < 8; ++kp) vfr[(dt + 2) % 3][kp] = *(const bf16x8*)(vp + kp * 32); }
;         f32x4 acc = zero4;
;         __builtin_amdgcn_s_setprio(1);
; #pragma unroll
;         for (int kp = 0; kp < 8; ++kp) acc = mfma16(vfr[dt % 3][kp], pf[kp], acc);
;         __builtin_amdgcn_s_setprio(0);
;         u32x2 w; w.x = cvt_pk_bf16(acc[0] * il, acc[1] * il); w.y = cvt_pk_bf16(acc[2] * il, acc[3] * il); if (do_store || acc[0] == 12345.678f) *(u32x2*)(qp + dt * 16 + 4 * fq) = w; }
; __global__ void __launch_bounds__(512, 2) mega(Args a) {
;     ...
;             for (int prep_ = 0; prep_ < PROBE_C2; ++prep_) for (int it = gw; it < (SEQ / 16) * 4; it += NGW) { const int hm = it & 3, t0 = (it >> 2) * 16;
;                 mem_task(ZMAIN, KVM + (size_t)b * 256 * 2048, VMT + (size_t)b * 4 * 256 * 256, hm, t0, lane, prep_ == PROBE_C2 - 1); }
	ds_read_b128 v[104:107], v179 offset:32768
	ds_read_b128 v[146:149], v179 offset:40960
	ds_read_b128 v[108:111], v179 offset:33792
	ds_read_b128 v[150:153], v179 offset:41984
	ds_read_b128 v[112:115], v179 offset:34816
	ds_read_b128 v[154:157], v179 offset:43008
	ds_read_b128 v[116:119], v179 offset:35840
	ds_read_b128 v[158:161], v179 offset:44032
	ds_read_b128 v[120:123], v179 offset:36864
	ds_read_b128 v[162:165], v179 offset:45056
	ds_read_b128 v[124:127], v179 offset:37888
	ds_read_b128 v[166:169], v179 offset:46080
	ds_read_b128 v[128:131], v179 offset:38912
	ds_read_b128 v[170:173], v179 offset:47104
	ds_read_b128 v[132:135], v179 offset:39936
	ds_read_b128 v[174:177], v179 offset:48128
	s_setprio 1
	s_waitcnt lgkmcnt(14)
	v_mfma_f32_16x16x32_bf16 v[192:195], v[104:107], v[32:35], 0
	v_mfma_f32_16x16x32_bf16 v[196:199], v[146:149], v[32:35], 0
	s_waitcnt lgkmcnt(12)
	v_mfma_f32_16x16x32_bf16 v[192:195], v[108:111], v[40:43], v[192:195]
	v_mfma_f32_16x16x32_bf16 v[196:199], v[150:153], v[40:43], v[196:199]
	s_waitcnt lgkmcnt(10)
	v_mfma_f32_16x16x32_bf16 v[192:195], v[112:115], v[48:51], v[192:195]
	v_mfma_f32_16x16x32_bf16 v[196:199], v[154:157], v[48:51], v[196:199]
	s_waitcnt lgkmcnt(8)
	v_mfma_f32_16x16x32_bf16 v[192:195], v[116:119], v[56:59], v[192:195]
	v_mfma_f32_16x16x32_bf16 v[196:199], v[158:161], v[56:59], v[196:199]
	s_waitcnt lgkmcnt(6)
	v_mfma_f32_16x16x32_bf16 v[192:195], v[120:123], v[72:75], v[192:195]
	v_mfma_f32_16x16x32_bf16 v[196:199], v[162:165], v[72:75], v[196:199]
	s_waitcnt lgkmcnt(4)
	v_mfma_f32_16x16x32_bf16 v[192:195], v[124:127], v[80:83], v[192:195]
	v_mfma_f32_16x16x32_bf16 v[196:199], v[166:169], v[80:83], v[196:199]
	s_waitcnt lgkmcnt(2)
	v_mfma_f32_16x16x32_bf16 v[192:195], v[128:131], v[88:91], v[192:195]
	v_mfma_f32_16x16x32_bf16 v[196:199], v[170:173], v[88:91], v[196:199]
	s_waitcnt lgkmcnt(0)
	v_mfma_f32_16x16x32_bf16 v[192:195], v[132:135], v[96:99], v[192:195]
	v_mfma_f32_16x16x32_bf16 v[196:199], v[174:177], v[96:99], v[196:199]
	s_setprio 0
	v_mul_f32_e32 v206, v191, v206
	v_mul_f32_e32 v207, v191, v207
	v_mul_f32_e32 v208, v191, v208
	v_mul_f32_e32 v209, v191, v209
	v_cvt_pk_bf16_f32 v206, v206, v207
	v_cvt_pk_bf16_f32 v207, v208, v209
	global_store_dwordx2 v[184:185], v[206:207], off offset:320
	v_mul_f32_e32 v210, v191, v210
	v_mul_f32_e32 v211, v191, v211
	v_mul_f32_e32 v212, v191, v212
	v_mul_f32_e32 v213, v191, v213
	v_cvt_pk_bf16_f32 v210, v210, v211
	v_cvt_pk_bf16_f32 v211, v212, v213
	global_store_dwordx2 v[184:185], v[210:211], off offset:352
	s_waitcnt vmcnt(12)
	s_barrier
	ds_read_b128 v[104:107], v179 offset:49152
	ds_read_b128 v[146:149], v179 offset:57344
	ds_read_b128 v[108:111], v179 offset:50176
	ds_read_b128 v[150:153], v179 offset:58368
	ds_read_b128 v[112:115], v179 offset:51200
	ds_read_b128 v[154:157], v179 offset:59392
	ds_read_b128 v[116:119], v179 offset:52224
	ds_read_b128 v[158:161], v179 offset:60416
	ds_read_b128 v[120:123], v179 offset:53248
	ds_read_b128 v[162:165], v179 offset:61440
	ds_read_b128 v[124:127], v179 offset:54272
	ds_read_b128 v[166:169], v179 offset:62464
	ds_read_b128 v[128:131], v179 offset:55296
	ds_read_b128 v[170:173], v179 offset:63488
	ds_read_b128 v[132:135], v179 offset:56320
	ds_read_b128 v[174:177], v179 offset:64512
	s_setprio 1
	s_waitcnt lgkmcnt(14)
	v_mfma_f32_16x16x32_bf16 v[206:209], v[104:107], v[32:35], 0
	v_mfma_f32_16x16x32_bf16 v[210:213], v[146:149], v[32:35], 0
	s_waitcnt lgkmcnt(12)
	v_mfma_f32_16x16x32_bf16 v[206:209], v[108:111], v[40:43], v[206:209]
	v_mfma_f32_16x16x32_bf16 v[210:213], v[150:153], v[40:43], v[210:213]
	s_waitcnt lgkmcnt(10)
	v_mfma_f32_16x16x32_bf16 v[206:209], v[112:115], v[48:51], v[206:209]
	v_mfma_f32_16x16x32_bf16 v[210:213], v[154:157], v[48:51], v[210:213]
	s_waitcnt lgkmcnt(8)
	v_mfma_f32_16x16x32_bf16 v[206:209], v[116:119], v[56:59], v[206:209]
	v_mfma_f32_16x16x32_bf16 v[210:213], v[158:161], v[56:59], v[210:213]
	s_waitcnt lgkmcnt(6)
	v_mfma_f32_16x16x32_bf16 v[206:209], v[120:123], v[72:75], v[206:209]
	v_mfma_f32_16x16x32_bf16 v[210:213], v[162:165], v[72:75], v[210:213]
	s_waitcnt lgkmcnt(4)
	v_mfma_f32_16x16x32_bf16 v[206:209], v[124:127], v[80:83], v[206:209]
	v_mfma_f32_16x16x32_bf16 v[210:213], v[166:169], v[80:83], v[210:213]
	s_waitcnt lgkmcnt(2)
	v_mfma_f32_16x16x32_bf16 v[206:209], v[128:131], v[88:91], v[206:209]
	v_mfma_f32_16x16x32_bf16 v[210:213], v[170:173], v[88:91], v[210:213]
	s_waitcnt lgkmcnt(0)
	v_mfma_f32_16x16x32_bf16 v[206:209], v[132:135], v[96:99], v[206:209]
	v_mfma_f32_16x16x32_bf16 v[210:213], v[174:177], v[96:99], v[210:213]
	s_setprio 0
	v_mul_f32_e32 v192, v191, v192
	v_mul_f32_e32 v193, v191, v193
	v_mul_f32_e32 v194, v191, v194
	v_mul_f32_e32 v195, v191, v195
	v_cvt_pk_bf16_f32 v192, v192, v193
	v_cvt_pk_bf16_f32 v193, v194, v195
	global_store_dwordx2 v[184:185], v[192:193], off offset:384
	v_mul_f32_e32 v196, v191, v196
	v_mul_f32_e32 v197, v191, v197
	v_mul_f32_e32 v198, v191, v198
	v_mul_f32_e32 v199, v191, v199
	v_cvt_pk_bf16_f32 v196, v196, v197
	v_cvt_pk_bf16_f32 v197, v198, v199
	global_store_dwordx2 v[184:185], v[196:197], off offset:416
	s_nop 7
	s_nop 7
	v_mul_f32_e32 v206, v191, v206
	v_mul_f32_e32 v207, v191, v207
	v_mul_f32_e32 v208, v191, v208
	v_mul_f32_e32 v209, v191, v209
	v_cvt_pk_bf16_f32 v206, v206, v207
	v_cvt_pk_bf16_f32 v207, v208, v209
	global_store_dwordx2 v[184:185], v[206:207], off offset:448
	v_mul_f32_e32 v210, v191, v210
	v_mul_f32_e32 v211, v191, v211
	v_mul_f32_e32 v212, v191, v212
	v_mul_f32_e32 v213, v191, v213
	v_cvt_pk_bf16_f32 v210, v210, v211
	v_cvt_pk_bf16_f32 v211, v212, v213
	global_store_dwordx2 v[184:185], v[210:211], off offset:480
	s_add_i32 s5, s5, s64
	s_cmpk_gt_i32 s5, 0x7ff
	s_cbranch_scc0 .LBB0_366
